# attention softmax cross-row max/sum reductions via v_permlane16_swap / v_permlane32_swap instead of four ds_bpermute round trips per item
# speedup vs baseline: 1.0035x; 1.0035x over previous
; __device__ __forceinline__ void attn_item(const Ctx& C, int it, int itn, u32x4 (&kv)[4], u32x4 (&vv)[4], u32x4 (&qv)[2]) {
;     ...
;     __syncthreads();
;     const int fr = lane & 15, quad = lane >> 4;
;     bf16x8 qf[2];
;     qf[0] = *(const bf16x8*)(Qs + (16 * w + fr) * 72 + 8 * quad); qf[1] = *(const bf16x8*)(Qs + (16 * w + fr) * 72 + 32 + 8 * quad);
;     f32x4 sc[9];
; #pragma unroll
;     for (int kt = 0; kt < 9; ++kt) { const bf16_t* kr = Ks + (16 * (w + kt) + fr) * 72 + 8 * quad;
;         const bf16x8 k0 = *(const bf16x8*)kr, k1 = *(const bf16x8*)(kr + 32);
;         f32x4 z4 = {0.f, 0.f, 0.f, 0.f};
;         z4 = __builtin_amdgcn_mfma_f32_16x16x32_bf16(k0, qf[0], z4, 0, 0, 0);
;         sc[kt] = __builtin_amdgcn_mfma_f32_16x16x32_bf16(k1, qf[1], z4, 0, 0, 0); }
;     const int a = 16 * w + fr;
;     float mx = -1e30f;
; #pragma unroll
;     for (int kt = 0; kt < 9; ++kt)
; #pragma unroll
;         for (int rg = 0; rg < 4; ++rg) { const int cidx = 16 * (w + kt) + 4 * quad + rg, rel = cidx - 64 - a, ik = 128 * jb - 64 + cidx;
;             const bool valid = (rel >= -64) && (rel <= 64) && (ik >= 0) && (ik < n);
;             const int bi = rel < -64 ? 0 : (rel > 64 ? 128 : rel + 64);
;             const float s = valid ? sc[kt][rg] * 0.125f + bt[bi] : -1e30f;
;             sc[kt][rg] = s; mx = fmaxf(mx, s); }
.LBB0_359:
	s_waitcnt lgkmcnt(0)
	s_barrier
	ds_read_b32 v212, v98
	ds_read_b32 v213, v100
	ds_read_b32 v214, v102
	ds_read_b32 v215, v104
	ds_read_b32 v223, v106
	ds_read_b32 v228, v108
	ds_read_b32 v229, v110
	ds_read_b32 v230, v112
	ds_read_b32 v231, v114
	ds_read_b32 v232, v116
	ds_read_b32 v233, v118
	ds_read_b32 v234, v120
	ds_read_b32 v235, v122
	ds_read_b32 v236, v124
	ds_read_b32 v237, v126
	ds_read_b32 v238, v128
	ds_read_b32 v240, v130
	ds_read_b32 v241, v132
	ds_read_b32 v242, v134
	ds_read_b32 v243, v136
	ds_read_b32 v244, v138
	ds_read_b32 v245, v140
	ds_read_b32 v246, v142
	ds_read_b32 v247, v144
	ds_read_b32 v248, v146
	ds_read_b32 v249, v148
	ds_read_b32 v250, v150
	ds_read_b128 v[40:43], v85 offset:36864
	ds_read_b128 v[194:197], v85 offset:36928
	ds_read_b128 v[44:47], v87
	ds_read_b128 v[48:51], v87 offset:64
	s_waitcnt lgkmcnt(1)
	v_mfma_f32_16x16x32_bf16 v[44:47], v[44:47], v[40:43], 0
	s_lshr_b32 s0, 32, s52
	s_and_b32 s47, s36, 31
	s_add_i32 s0, s0, -1
	s_waitcnt lgkmcnt(0)
	v_mfma_f32_16x16x32_bf16 v[74:77], v[48:51], v[194:197], v[44:47]
	s_nop 2
	ds_read_b128 v[44:47], v173
	ds_read_b128 v[48:51], v173 offset:64
	s_and_b32 s0, s0, s47
	s_lshl_b32 s46, s0, 7
	s_waitcnt lgkmcnt(1)
	v_mfma_f32_16x16x32_bf16 v[44:47], v[44:47], v[40:43], 0
	s_sub_i32 s48, s46, 64
	v_add_u32_e32 v64, s48, v89
	v_readlane_b32 s0, v255, 7
	s_waitcnt lgkmcnt(0)
	v_mfma_f32_16x16x32_bf16 v[70:73], v[48:51], v[194:197], v[44:47]
	s_nop 2
	ds_read_b128 v[44:47], v174
	ds_read_b128 v[48:51], v174 offset:64
	s_lshr_b32 s53, 0x1000, s52
	v_cmp_lt_i32_e32 vcc, -1, v64
	s_waitcnt lgkmcnt(1)
	v_mfma_f32_16x16x32_bf16 v[44:47], v[44:47], v[40:43], 0
	v_readlane_b32 s1, v255, 8
	s_and_b64 s[0:1], s[0:1], vcc
	v_cmp_gt_i32_e32 vcc, s53, v64
	s_waitcnt lgkmcnt(0)
	v_mfma_f32_16x16x32_bf16 v[66:69], v[48:51], v[194:197], v[44:47]
	s_nop 2
	ds_read_b128 v[44:47], v175
	ds_read_b128 v[48:51], v175 offset:64
	s_and_b64 s[68:69], s[0:1], vcc
	s_waitcnt lgkmcnt(1)
	v_mfma_f32_16x16x32_bf16 v[44:47], v[44:47], v[40:43], 0
	s_waitcnt lgkmcnt(0)
	v_mfma_f32_16x16x32_bf16 v[60:63], v[48:51], v[194:197], v[44:47]
	s_nop 5
	ds_read_b128 v[44:47], v176
	ds_read_b128 v[48:51], v176 offset:64
	s_waitcnt lgkmcnt(1)
	v_mfma_f32_16x16x32_bf16 v[44:47], v[44:47], v[40:43], 0
	s_waitcnt lgkmcnt(0)
	v_mfma_f32_16x16x32_bf16 v[56:59], v[48:51], v[194:197], v[44:47]
	s_nop 5
	ds_read_b128 v[44:47], v177
	ds_read_b128 v[48:51], v177 offset:64
	s_waitcnt lgkmcnt(1)
	v_mfma_f32_16x16x32_bf16 v[44:47], v[44:47], v[40:43], 0
	s_waitcnt lgkmcnt(0)
	v_mfma_f32_16x16x32_bf16 v[52:55], v[48:51], v[194:197], v[44:47]
	s_nop 5
	ds_read_b128 v[44:47], v183
	ds_read_b128 v[48:51], v183 offset:64
	s_waitcnt lgkmcnt(1)
	v_mfma_f32_16x16x32_bf16 v[44:47], v[44:47], v[40:43], 0
	s_waitcnt lgkmcnt(0)
	v_mfma_f32_16x16x32_bf16 v[48:51], v[48:51], v[194:197], v[44:47]
	s_nop 5
	ds_read_b128 v[44:47], v192
	ds_read_b128 v[198:201], v192 offset:64
	s_waitcnt lgkmcnt(1)
	v_mfma_f32_16x16x32_bf16 v[44:47], v[44:47], v[40:43], 0
	s_waitcnt lgkmcnt(0)
	v_mfma_f32_16x16x32_bf16 v[44:47], v[198:201], v[194:197], v[44:47]
	ds_read_b128 v[198:201], v193
	ds_read_b128 v[202:205], v193 offset:64
	s_waitcnt lgkmcnt(1)
	v_mfma_f32_16x16x32_bf16 v[40:43], v[198:201], v[40:43], 0
	s_waitcnt lgkmcnt(0)
	v_mfma_f32_16x16x32_bf16 v[40:43], v[202:205], v[194:197], v[40:43]
	v_lshrrev_b32_e32 v178, 6, v224
	v_lshlrev_b32_e32 v178, 4, v178
	v_and_b32_e32 v179, 15, v224
	v_add_u32_e32 v179, v178, v179
	s_sub_i32 s0, 0, s48
	v_max_i32_e32 v180, s0, v179
	s_sub_i32 s1, s53, s48
	s_add_i32 s1, s1, -1
	v_add_u32_e32 v179, 0x80, v179
	v_min_i32_e32 v181, s1, v179
	v_bfe_u32 v179, v224, 4, 2
	v_lshl_add_u32 v178, v179, 2, v178
	v_sub_u32_e32 v188, v178, v180
	v_sub_u32_e32 v189, v181, v180
	v_mov_b32_e32 v179, 0xf149f2ca
	v_add_u32_e32 v190, 0, v188
	v_cmp_ge_u32_e32 vcc, v189, v190
	v_fmac_f32_e32 v212, 0x3e000000, v74
	v_add_u32_e32 v191, 1, v188
	v_cndmask_b32_e32 v195, v179, v212, vcc
	ds_read_b32 v212, v152
	v_cmp_ge_u32_e32 vcc, v189, v191
	v_fmac_f32_e32 v213, 0x3e000000, v75
	v_add_u32_e32 v190, 2, v188
	v_cndmask_b32_e32 v91, v179, v213, vcc
	ds_read_b32 v213, v154
	v_cmp_ge_u32_e32 vcc, v189, v190
	v_fmac_f32_e32 v214, 0x3e000000, v76
	v_add_u32_e32 v191, 3, v188
	v_cndmask_b32_e32 v194, v179, v214, vcc
	ds_read_b32 v214, v156
	v_cmp_ge_u32_e32 vcc, v189, v191
	v_fmac_f32_e32 v215, 0x3e000000, v77
	v_add_u32_e32 v190, 16, v188
	v_cndmask_b32_e32 v79, v179, v215, vcc
	ds_read_b32 v215, v158
	v_cmp_ge_u32_e32 vcc, v189, v190
	v_fmac_f32_e32 v223, 0x3e000000, v70
	v_add_u32_e32 v191, 17, v188
	v_cndmask_b32_e32 v74, v179, v223, vcc
	ds_read_b32 v223, v160
	v_cmp_ge_u32_e32 vcc, v189, v191
	v_fmac_f32_e32 v228, 0x3e000000, v71
	v_add_u32_e32 v190, 18, v188
	v_cndmask_b32_e32 v64, v179, v228, vcc
	ds_read_b32 v228, v162
	v_cmp_ge_u32_e32 vcc, v189, v190
	v_fmac_f32_e32 v229, 0x3e000000, v72
	v_add_u32_e32 v191, 19, v188
	v_cndmask_b32_e32 v75, v179, v229, vcc
	ds_read_b32 v229, v164
	v_cmp_ge_u32_e32 vcc, v189, v191
	v_fmac_f32_e32 v230, 0x3e000000, v73
	v_add_u32_e32 v190, 32, v188
	v_cndmask_b32_e32 v70, v179, v230, vcc
	ds_read_b32 v230, v166
	v_cmp_ge_u32_e32 vcc, v189, v190
	v_fmac_f32_e32 v231, 0x3e000000, v66
	v_add_u32_e32 v191, 33, v188
	v_cndmask_b32_e32 v72, v179, v231, vcc
	ds_read_b32 v231, v168
	v_cmp_ge_u32_e32 vcc, v189, v191
	v_fmac_f32_e32 v232, 0x3e000000, v67
	v_add_u32_e32 v190, 34, v188
	v_cndmask_b32_e32 v71, v179, v232, vcc
	v_cmp_ge_u32_e32 vcc, v189, v190
	v_fmac_f32_e32 v233, 0x3e000000, v68
	v_add_u32_e32 v191, 35, v188
	v_cndmask_b32_e32 v73, v179, v233, vcc
	v_cmp_ge_u32_e32 vcc, v189, v191
; __device__ __forceinline__ unsigned cvt_pk_bf16(float lo, float hi) { f32x2_t v = {lo, hi}; bf2_t r = __builtin_convertvector(v, bf2_t); return __builtin_bit_cast(unsigned, r); }
; __device__ __forceinline__ s16x4_t lds_tr_b64(const bf16_t* p) { return __builtin_amdgcn_ds_read_tr16_b64_v4i16((LAS s16x4_t*)p); }
; __device__ __forceinline__ void attn_item(const Ctx& C, int it, int itn, u32x4 (&kv)[4], u32x4 (&vv)[4], u32x4 (&qv)[2]) {
;     ...
;         for (int rg = 0; rg < 4; ++rg) { const int cidx = 16 * (w + kt) + 4 * quad + rg, rel = cidx - 64 - a, ik = 128 * jb - 64 + cidx;
;             const bool valid = (rel >= -64) && (rel <= 64) && (ik >= 0) && (ik < n);
;             const int bi = rel < -64 ? 0 : (rel > 64 ? 128 : rel + 64);
;             const float s = valid ? sc[kt][rg] * 0.125f + bt[bi] : -1e30f;
;             sc[kt][rg] = s; mx = fmaxf(mx, s); }
;     mx = fmaxf(mx, __shfl_xor(mx, 16)); mx = fmaxf(mx, __shfl_xor(mx, 32));
;     float lsum = 0.f;
; #pragma unroll
;     for (int kt = 0; kt < 9; ++kt)
; #pragma unroll
;         for (int rg = 0; rg < 4; ++rg) { const float s = sc[kt][rg]; const float p = (s > -1e29f) ? __expf(s - mx) : 0.f; sc[kt][rg] = p; lsum += p; }
;     lsum += __shfl_xor(lsum, 16); lsum += __shfl_xor(lsum, 32);
;     f32x4 oo[4];
; #pragma unroll
;     for (int dt = 0; dt < 4; ++dt) oo[dt] = (f32x4){0.f, 0.f, 0.f, 0.f};
; #pragma unroll
;     for (int pp = 0; pp < 5; ++pp) { const int ktA = 2 * pp, ktB = 2 * pp + 1, ktBc = ktB < 9 ? ktB : 8;
;         union { bf16x8 v; unsigned u[4]; } pf;
;         pf.u[0] = cvt_pk_bf16(sc[ktA][0], sc[ktA][1]); pf.u[1] = cvt_pk_bf16(sc[ktA][2], sc[ktA][3]);
;         if (ktB < 9) { pf.u[2] = cvt_pk_bf16(sc[ktBc][0], sc[ktBc][1]); pf.u[3] = cvt_pk_bf16(sc[ktBc][2], sc[ktBc][3]); } else { pf.u[2] = 0u; pf.u[3] = 0u; }
; #pragma unroll
;         for (int dt = 0; dt < 4; ++dt) { const bf16_t* vr = Vs + (16 * w + 4 * quad + (fr >> 2)) * 72 + 16 * dt + 4 * (fr & 3);
;             union { bf16x8 v; s16x4_t h[2]; } vf; vf.h[0] = lds_tr_b64(vr + 16 * ktA * 72); vf.h[1] = lds_tr_b64(vr + 16 * ktBc * 72);
	v_fmac_f32_e32 v234, 0x3e000000, v69
	v_add_u32_e32 v190, 48, v188
	v_cndmask_b32_e32 v66, v179, v234, vcc
	v_cmp_ge_u32_e32 vcc, v189, v190
	v_fmac_f32_e32 v235, 0x3e000000, v60
	v_add_u32_e32 v191, 49, v188
	v_cndmask_b32_e32 v69, v179, v235, vcc
	v_cmp_ge_u32_e32 vcc, v189, v191
	v_fmac_f32_e32 v236, 0x3e000000, v61
	v_add_u32_e32 v190, 50, v188
	v_cndmask_b32_e32 v67, v179, v236, vcc
	v_cmp_ge_u32_e32 vcc, v189, v190
	v_fmac_f32_e32 v237, 0x3e000000, v62
	v_add_u32_e32 v191, 51, v188
	v_cndmask_b32_e32 v68, v179, v237, vcc
	v_cmp_ge_u32_e32 vcc, v189, v191
	v_fmac_f32_e32 v238, 0x3e000000, v63
	v_add_u32_e32 v190, 64, v188
	v_cndmask_b32_e32 v60, v179, v238, vcc
	v_cmp_ge_u32_e32 vcc, v189, v190
	v_fmac_f32_e32 v240, 0x3e000000, v56
	v_add_u32_e32 v191, 0x41, v188
	v_cndmask_b32_e32 v62, v179, v240, vcc
	v_cmp_ge_u32_e32 vcc, v189, v191
	v_fmac_f32_e32 v241, 0x3e000000, v57
	v_add_u32_e32 v190, 0x42, v188
	v_cndmask_b32_e32 v61, v179, v241, vcc
	v_cmp_ge_u32_e32 vcc, v189, v190
	v_fmac_f32_e32 v242, 0x3e000000, v58
	v_add_u32_e32 v191, 0x43, v188
	v_cndmask_b32_e32 v63, v179, v242, vcc
	v_cmp_ge_u32_e32 vcc, v189, v191
	v_fmac_f32_e32 v243, 0x3e000000, v59
	v_add_u32_e32 v190, 0x50, v188
	v_cndmask_b32_e32 v57, v179, v243, vcc
	v_cmp_ge_u32_e32 vcc, v189, v190
	v_fmac_f32_e32 v244, 0x3e000000, v52
	v_add_u32_e32 v191, 0x51, v188
	v_cndmask_b32_e32 v59, v179, v244, vcc
	v_cmp_ge_u32_e32 vcc, v189, v191
	v_fmac_f32_e32 v245, 0x3e000000, v53
	v_add_u32_e32 v190, 0x52, v188
	v_cndmask_b32_e32 v56, v179, v245, vcc
	v_cmp_ge_u32_e32 vcc, v189, v190
	v_fmac_f32_e32 v246, 0x3e000000, v54
	v_add_u32_e32 v191, 0x53, v188
	v_cndmask_b32_e32 v58, v179, v246, vcc
	v_cmp_ge_u32_e32 vcc, v189, v191
	v_fmac_f32_e32 v247, 0x3e000000, v55
	v_add_u32_e32 v190, 0x60, v188
	v_cndmask_b32_e32 v53, v179, v247, vcc
	v_cmp_ge_u32_e32 vcc, v189, v190
	v_fmac_f32_e32 v248, 0x3e000000, v48
	v_add_u32_e32 v191, 0x61, v188
	v_cndmask_b32_e32 v55, v179, v248, vcc
	v_cmp_ge_u32_e32 vcc, v189, v191
	v_fmac_f32_e32 v249, 0x3e000000, v49
	v_add_u32_e32 v190, 0x62, v188
	v_cndmask_b32_e32 v52, v179, v249, vcc
	v_cmp_ge_u32_e32 vcc, v189, v190
	v_fmac_f32_e32 v250, 0x3e000000, v50
	v_add_u32_e32 v191, 0x63, v188
	v_cndmask_b32_e32 v54, v179, v250, vcc
	s_waitcnt lgkmcnt(0)
	v_cmp_ge_u32_e32 vcc, v189, v191
	v_fmac_f32_e32 v212, 0x3e000000, v51
	v_add_u32_e32 v190, 0x70, v188
	v_cndmask_b32_e32 v49, v179, v212, vcc
	v_cmp_ge_u32_e32 vcc, v189, v190
	v_fmac_f32_e32 v213, 0x3e000000, v44
	v_add_u32_e32 v191, 0x71, v188
	v_cndmask_b32_e32 v50, v179, v213, vcc
	v_cmp_ge_u32_e32 vcc, v189, v191
	v_fmac_f32_e32 v214, 0x3e000000, v45
	v_add_u32_e32 v190, 0x72, v188
	v_cndmask_b32_e32 v48, v179, v214, vcc
	v_cmp_ge_u32_e32 vcc, v189, v190
	v_fmac_f32_e32 v215, 0x3e000000, v46
	v_add_u32_e32 v191, 0x73, v188
	v_cndmask_b32_e32 v45, v179, v215, vcc
	v_cmp_ge_u32_e32 vcc, v189, v191
	v_fmac_f32_e32 v223, 0x3e000000, v47
	v_add_u32_e32 v190, 0x80, v188
	v_cndmask_b32_e32 v44, v179, v223, vcc
	v_cmp_ge_u32_e32 vcc, v189, v190
	v_fmac_f32_e32 v228, 0x3e000000, v40
	v_add_u32_e32 v191, 0x81, v188
	v_cndmask_b32_e32 v47, v179, v228, vcc
	v_cmp_ge_u32_e32 vcc, v189, v191
	v_fmac_f32_e32 v229, 0x3e000000, v41
	v_add_u32_e32 v190, 0x82, v188
	v_cndmask_b32_e32 v46, v179, v229, vcc
	v_cmp_ge_u32_e32 vcc, v189, v190
	v_fmac_f32_e32 v230, 0x3e000000, v42
	v_add_u32_e32 v191, 0x83, v188
	v_cndmask_b32_e32 v51, v179, v230, vcc
	v_cmp_ge_u32_e32 vcc, v189, v191
	v_fmac_f32_e32 v231, 0x3e000000, v43
	s_nop 0
	v_cndmask_b32_e32 v41, v179, v231, vcc
	s_mov_b32 s0, 0xf149f2ca
	v_max3_f32 v40, v195, s0, v91
	v_max3_f32 v40, v40, v194, v79
	v_max3_f32 v40, v40, v74, v64
	v_max3_f32 v40, v40, v75, v70
	v_max3_f32 v40, v40, v72, v71
	v_max3_f32 v40, v40, v73, v66
	v_max3_f32 v40, v40, v69, v67
	v_max3_f32 v40, v40, v68, v60
	v_max3_f32 v40, v40, v62, v61
	v_max3_f32 v40, v40, v63, v57
	v_max3_f32 v40, v40, v59, v56
	v_max3_f32 v40, v40, v58, v53
	v_max3_f32 v40, v40, v55, v52
	v_max3_f32 v40, v40, v54, v49
	v_max3_f32 v40, v40, v50, v48
	v_max3_f32 v40, v40, v45, v44
	v_max3_f32 v40, v40, v47, v46
	v_max3_f32 v40, v40, v51, v41
	v_mov_b32_e32 v42, v40
	v_mov_b32_e32 v99, v40
	s_mov_b32 s1, 0x3fb8aa3b
	s_sub_i32 s0, 5, s52
	s_lshr_b32 s0, s47, s0
	s_waitcnt lgkmcnt(0)
	v_permlane16_swap_b32_e32 v42, v99
	v_max_f32_e32 v40, v42, v99
	v_mov_b32_e32 v42, v40
	v_mov_b32_e32 v99, v40
	s_nop 1
	s_waitcnt lgkmcnt(0)
	v_permlane32_swap_b32_e32 v42, v99
	v_max_f32_e32 v42, v42, v99
	v_mul_f32_e32 v178, 0xbfb8aa3b, v42
	v_fma_f32 v40, v195, s1, v178
	v_fma_f32 v43, v91, s1, v178
	v_exp_f32_e32 v40, v40
	v_exp_f32_e32 v43, v43
	v_add_f32_e32 v76, 0, v40
	s_nop 0
	v_add_f32_e32 v77, v43, v76
	v_fma_f32 v76, v194, s1, v178
	v_exp_f32_e32 v76, v76
	v_cvt_pk_bf16_f32 v196, v40, v43
	s_nop 0
	v_add_f32_e32 v91, v76, v77
	v_fma_f32 v77, v79, s1, v178
	v_exp_f32_e32 v77, v77
	s_nop 1
	v_fma_f32 v74, v74, s1, v178
	v_exp_f32_e32 v74, v74
	v_add_f32_e32 v79, v77, v91
	v_cvt_pk_bf16_f32 v197, v76, v77
	v_fma_f32 v64, v64, s1, v178
	v_exp_f32_e32 v64, v64
	v_add_f32_e32 v91, v74, v79
	v_mov_b32_e32 v79, v64
	v_fma_f32 v75, v75, s1, v178
	v_exp_f32_e32 v75, v75
	v_add_f32_e32 v64, v79, v91
	v_cvt_pk_bf16_f32 v198, v74, v79
	v_fma_f32 v70, v70, s1, v178
	v_exp_f32_e32 v70, v70
	v_add_f32_e32 v64, v75, v64
	v_mov_b32_e32 v91, v70
	v_add_f32_e32 v70, v91, v64
	v_fma_f32 v64, v72, s1, v178
	v_exp_f32_e32 v64, v64
	v_cvt_pk_bf16_f32 v199, v75, v91
	ds_read_b64_tr_b16 v[76:77], v171 offset:57600
	ds_read_b64_tr_b16 v[74:75], v171 offset:55296
	ds_read_b64_tr_b16 v[200:201], v171 offset:55328
	v_add_f32_e32 v72, v64, v70
	v_fma_f32 v70, v71, s1, v178
	v_fma_f32 v71, v73, s1, v178
	v_exp_f32_e32 v70, v70
	v_exp_f32_e32 v71, v71
	ds_read_b64_tr_b16 v[202:203], v171 offset:57632
	v_add_f32_e32 v72, v70, v72
	ds_read_b64_tr_b16 v[204:205], v171 offset:55360
	ds_read_b64_tr_b16 v[206:207], v171 offset:57664
	v_fma_f32 v66, v66, s1, v178
	v_exp_f32_e32 v66, v66
	v_add_f32_e32 v72, v71, v72
	ds_read_b64_tr_b16 v[208:209], v171 offset:55392
	ds_read_b64_tr_b16 v[210:211], v171 offset:57696
	s_waitcnt lgkmcnt(6)
; __device__ __forceinline__ unsigned cvt_pk_bf16(float lo, float hi) { f32x2_t v = {lo, hi}; bf2_t r = __builtin_convertvector(v, bf2_t); return __builtin_bit_cast(unsigned, r); }
; __device__ __forceinline__ s16x4_t lds_tr_b64(const bf16_t* p) { return __builtin_amdgcn_ds_read_tr16_b64_v4i16((LAS s16x4_t*)p); }
; __device__ __forceinline__ void attn_item(const Ctx& C, int it, int itn, u32x4 (&kv)[4], u32x4 (&vv)[4], u32x4 (&qv)[2]) {
;     ...
;     float lsum = 0.f;
; #pragma unroll
;     for (int kt = 0; kt < 9; ++kt)
; #pragma unroll
;         for (int rg = 0; rg < 4; ++rg) { const float s = sc[kt][rg]; const float p = (s > -1e29f) ? __expf(s - mx) : 0.f; sc[kt][rg] = p; lsum += p; }
;     lsum += __shfl_xor(lsum, 16); lsum += __shfl_xor(lsum, 32);
;     f32x4 oo[4];
; #pragma unroll
;     for (int dt = 0; dt < 4; ++dt) oo[dt] = (f32x4){0.f, 0.f, 0.f, 0.f};
; #pragma unroll
;     for (int pp = 0; pp < 5; ++pp) { const int ktA = 2 * pp, ktB = 2 * pp + 1, ktBc = ktB < 9 ? ktB : 8;
;         union { bf16x8 v; unsigned u[4]; } pf;
;         pf.u[0] = cvt_pk_bf16(sc[ktA][0], sc[ktA][1]); pf.u[1] = cvt_pk_bf16(sc[ktA][2], sc[ktA][3]);
;         if (ktB < 9) { pf.u[2] = cvt_pk_bf16(sc[ktBc][0], sc[ktBc][1]); pf.u[3] = cvt_pk_bf16(sc[ktBc][2], sc[ktBc][3]); } else { pf.u[2] = 0u; pf.u[3] = 0u; }
; #pragma unroll
;         for (int dt = 0; dt < 4; ++dt) { const bf16_t* vr = Vs + (16 * w + 4 * quad + (fr >> 2)) * 72 + 16 * dt + 4 * (fr & 3);
;             union { bf16x8 v; s16x4_t h[2]; } vf; vf.h[0] = lds_tr_b64(vr + 16 * ktA * 72); vf.h[1] = lds_tr_b64(vr + 16 * ktBc * 72);
;             oo[dt] = __builtin_amdgcn_mfma_f32_16x16x32_bf16(vf.v, pf.v, oo[dt], 0, 0, 0); } }
;     const float inv = 1.0f / lsum;
	v_mfma_f32_16x16x32_bf16 v[74:77], v[74:77], v[196:199], 0
	v_fma_f32 v69, v69, s1, v178
	v_exp_f32_e32 v69, v69
	v_add_f32_e32 v72, v66, v72
	s_waitcnt lgkmcnt(4)
	v_mfma_f32_16x16x32_bf16 v[200:203], v[200:203], v[196:199], 0
	v_mov_b32_e32 v91, v65
	v_fma_f32 v67, v67, s1, v178
	v_exp_f32_e32 v67, v67
	v_add_f32_e32 v72, v69, v72
	s_waitcnt lgkmcnt(2)
	v_mfma_f32_16x16x32_bf16 v[204:207], v[204:207], v[196:199], 0
	v_fma_f32 v68, v68, s1, v178
	v_exp_f32_e32 v68, v68
	v_add_f32_e32 v72, v67, v72
	s_waitcnt lgkmcnt(0)
	v_mfma_f32_16x16x32_bf16 v[196:199], v[208:211], v[196:199], 0
	v_cvt_pk_bf16_f32 v209, v71, v66
	v_fma_f32 v60, v60, s1, v178
	v_exp_f32_e32 v60, v60
	v_add_f32_e32 v73, v68, v72
	v_cvt_pk_bf16_f32 v210, v69, v67
	v_cvt_pk_bf16_f32 v208, v64, v70
	v_mov_b32_e32 v72, v60
	v_fma_f32 v60, v62, s1, v178
	v_exp_f32_e32 v60, v60
	v_add_f32_e32 v73, v72, v73
	v_cvt_pk_bf16_f32 v211, v68, v72
	v_fma_f32 v61, v61, s1, v178
	v_exp_f32_e32 v61, v61
	v_add_f32_e32 v62, v60, v73
	ds_read_b64_tr_b16 v[66:67], v171 offset:59904
	ds_read_b64_tr_b16 v[68:69], v171 offset:62208
	s_waitcnt lgkmcnt(0)
	v_mfma_f32_16x16x32_bf16 v[66:69], v[66:69], v[208:211], v[74:77]
	v_add_f32_e32 v73, v61, v62
	v_fma_f32 v62, v63, s1, v178
	v_exp_f32_e32 v62, v62
	ds_read_b64_tr_b16 v[74:75], v171 offset:59936
	ds_read_b64_tr_b16 v[76:77], v171 offset:62240
	s_waitcnt lgkmcnt(0)
	v_mfma_f32_16x16x32_bf16 v[74:77], v[74:77], v[208:211], v[200:203]
	v_fma_f32 v57, v57, s1, v178
	v_exp_f32_e32 v57, v57
	v_add_f32_e32 v63, v62, v73
	ds_read_b64_tr_b16 v[200:201], v171 offset:59968
	ds_read_b64_tr_b16 v[202:203], v171 offset:62272
	s_waitcnt lgkmcnt(0)
	v_mfma_f32_16x16x32_bf16 v[200:203], v[200:203], v[208:211], v[204:207]
	v_fma_f32 v59, v59, s1, v178
	v_exp_f32_e32 v59, v59
	v_add_f32_e32 v63, v57, v63
	ds_read_b64_tr_b16 v[204:205], v171 offset:60000
	ds_read_b64_tr_b16 v[206:207], v171 offset:62304
	v_cvt_pk_bf16_f32 v60, v60, v61
	v_fma_f32 v56, v56, s1, v178
	v_exp_f32_e32 v56, v56
	v_add_f32_e32 v63, v59, v63
	v_cvt_pk_bf16_f32 v61, v62, v57
	s_waitcnt lgkmcnt(0)
	v_mfma_f32_16x16x32_bf16 v[196:199], v[204:207], v[208:211], v[196:199]
	v_fma_f32 v58, v58, s1, v178
	v_exp_f32_e32 v58, v58
	v_add_f32_e32 v63, v56, v63
	v_cvt_pk_bf16_f32 v62, v59, v56
	v_mov_b32_e32 v64, v65
	v_fma_f32 v53, v53, s1, v178
	v_exp_f32_e32 v53, v53
	v_add_f32_e32 v73, v58, v63
	v_mov_b32_e32 v63, v53
	v_fma_f32 v53, v55, s1, v178
	v_exp_f32_e32 v53, v53
	v_add_f32_e32 v73, v63, v73
	v_cvt_pk_bf16_f32 v63, v58, v63
	v_fma_f32 v52, v52, s1, v178
	v_exp_f32_e32 v52, v52
	ds_read_b64_tr_b16 v[56:57], v171 offset:64512
	ds_read_b64_tr_b16 v[58:59], v172 offset:11520
	ds_read_b64_tr_b16 v[70:71], v172 offset:11552
	v_add_f32_e32 v55, v53, v73
	s_waitcnt lgkmcnt(1)
	v_mfma_f32_16x16x32_bf16 v[56:59], v[56:59], v[60:63], v[66:69]
	v_fma_f32 v54, v54, s1, v178
	v_exp_f32_e32 v54, v54
	v_add_f32_e32 v55, v52, v55
	ds_read_b64_tr_b16 v[68:69], v171 offset:64544
	s_waitcnt lgkmcnt(0)
	v_mfma_f32_16x16x32_bf16 v[66:69], v[68:71], v[60:63], v[74:77]
	v_fma_f32 v49, v49, s1, v178
	v_exp_f32_e32 v49, v49
	v_add_f32_e32 v55, v54, v55
	ds_read_b64_tr_b16 v[74:75], v171 offset:64576
	ds_read_b64_tr_b16 v[76:77], v172 offset:11584
	s_waitcnt lgkmcnt(0)
	v_mfma_f32_16x16x32_bf16 v[74:77], v[74:77], v[60:63], v[200:203]
	v_fma_f32 v50, v50, s1, v178
	v_exp_f32_e32 v50, v50
	v_add_f32_e32 v55, v49, v55
	ds_read_b64_tr_b16 v[200:201], v171 offset:64608
	ds_read_b64_tr_b16 v[202:203], v172 offset:11616
	v_cvt_pk_bf16_f32 v52, v53, v52
	v_fma_f32 v48, v48, s1, v178
	v_exp_f32_e32 v48, v48
	v_add_f32_e32 v73, v50, v55
	v_cvt_pk_bf16_f32 v53, v54, v49
	s_waitcnt lgkmcnt(0)
	v_mfma_f32_16x16x32_bf16 v[60:63], v[200:203], v[60:63], v[196:199]
	v_mov_b32_e32 v55, v48
	v_fma_f32 v45, v45, s1, v178
	v_exp_f32_e32 v45, v45
	v_add_f32_e32 v48, v55, v73
	v_cvt_pk_bf16_f32 v54, v50, v55
	v_mov_b32_e32 v73, v45
	v_fma_f32 v44, v44, s1, v178
	v_exp_f32_e32 v44, v44
	v_add_f32_e32 v45, v73, v48
	v_mov_b32_e32 v194, v44
	v_add_f32_e32 v44, v194, v45
	v_fma_f32 v45, v47, s1, v178
	v_cvt_pk_bf16_f32 v55, v73, v194
	ds_read_b64_tr_b16 v[70:71], v172 offset:13824
	ds_read_b64_tr_b16 v[72:73], v172 offset:16128
	v_exp_f32_e32 v45, v45
	s_waitcnt lgkmcnt(0)
	v_mfma_f32_16x16x32_bf16 v[56:59], v[70:73], v[52:55], v[56:59]
	ds_read_b64_tr_b16 v[70:71], v172 offset:13856
	ds_read_b64_tr_b16 v[72:73], v172 offset:16160
	v_fma_f32 v46, v46, s1, v178
	v_fma_f32 v47, v51, s1, v178
	v_exp_f32_e32 v46, v46
	v_exp_f32_e32 v47, v47
	s_waitcnt lgkmcnt(0)
	v_mfma_f32_16x16x32_bf16 v[66:69], v[70:73], v[52:55], v[66:69]
	ds_read_b64_tr_b16 v[70:71], v172 offset:13888
	ds_read_b64_tr_b16 v[72:73], v172 offset:16192
	s_waitcnt lgkmcnt(0)
	v_mfma_f32_16x16x32_bf16 v[70:73], v[70:73], v[52:55], v[74:77]
	v_fma_f32 v41, v41, s1, v178
	v_exp_f32_e32 v41, v41
	ds_read_b64_tr_b16 v[74:75], v172 offset:13920
	ds_read_b64_tr_b16 v[76:77], v172 offset:16224
	v_add_f32_e32 v44, v45, v44
	v_add_f32_e32 v44, v46, v44
	v_mov_b32_e32 v48, v41
	v_add_f32_e32 v44, v47, v44
	s_waitcnt lgkmcnt(0)
	v_mfma_f32_16x16x32_bf16 v[50:53], v[74:77], v[52:55], v[60:63]
	v_add_f32_e32 v41, v48, v44
	v_mov_b32_e32 v44, v41
	v_mov_b32_e32 v99, v41
	ds_read_b64_tr_b16 v[54:55], v172 offset:18464
	v_cvt_pk_bf16_f32 v62, v45, v46
	v_cvt_pk_bf16_f32 v63, v47, v48
	ds_read_b64_tr_b16 v[46:47], v172 offset:18432
	v_permlane16_swap_b32_e32 v44, v99
	v_add_f32_e32 v41, v44, v99
	v_mov_b32_e32 v44, v41
	v_mov_b32_e32 v99, v41
	s_lshl_b32 s1, s51, 12
	s_or_b32 s0, s0, s1
	s_waitcnt lgkmcnt(0)
	v_mov_b32_e32 v48, v46
	v_mov_b32_e32 v49, v47
	v_permlane32_swap_b32_e32 v44, v99
	v_add_f32_e32 v41, v44, v99
	v_div_scale_f32 v40, s[48:49], v41, v41, 1.0
	v_mfma_f32_16x16x32_bf16 v[46:49], v[46:49], v[62:65], v[56:59]
	v_rcp_f32_e32 v43, v40
	s_nop 1
	v_mov_b32_e32 v56, v54
	v_mov_b32_e32 v57, v55
	ds_read_b64_tr_b16 v[58:59], v172 offset:18496
	v_fma_f32 v44, -v40, v43, 1.0
	v_mfma_f32_16x16x32_bf16 v[54:57], v[54:57], v[62:65], v[66:69]
	v_fmac_f32_e32 v43, v44, v43
	s_nop 1
	ds_read_b64_tr_b16 v[66:67], v172 offset:18528
	s_waitcnt lgkmcnt(1)
	v_mov_b32_e32 v60, v58
	v_mov_b32_e32 v61, v59
	v_div_scale_f32 v44, vcc, 1.0, v41, 1.0
	s_waitcnt lgkmcnt(0)
	v_mov_b32_e32 v68, v66
	v_mov_b32_e32 v69, v67
	v_mul_f32_e32 v45, v44, v43
	v_mfma_f32_16x16x32_bf16 v[58:61], v[58:61], v[62:65], v[70:73]
	s_barrier
; __device__ __forceinline__ unsigned cvt_pk_bf16(float lo, float hi) { f32x2_t v = {lo, hi}; bf2_t r = __builtin_convertvector(v, bf2_t); return __builtin_bit_cast(unsigned, r); }
;     __device__ __forceinline__ float* fp(size_t off) const { return (float*)(ws + off); }
; __device__ __forceinline__ void attn_item(const Ctx& C, int it, int itn, u32x4 (&kv)[4], u32x4 (&vv)[4], u32x4 (&qv)[2]) {
;     ...
;     const float inv = 1.0f / lsum;
;     const size_t tok = (size_t)(b * SEQ + r + dil * (128 * jb + a));
;     __syncthreads();
; #pragma unroll
;     for (int dt = 0; dt < 4; ++dt) { u32x2 o; o.x = cvt_pk_bf16(oo[dt][0] * inv, oo[dt][1] * inv); o.y = cvt_pk_bf16(oo[dt][2] * inv, oo[dt][3] * inv);
;         *(u32x2*)(pd + tok * 2304 + hq * 64 + 16 * dt + 4 * quad) = o; }
;     if (quad == 0) C.fp(OFF_LSE)[((size_t)g * M_TOK + tok) * 4 + (hq & 3)] = mx + __logf(lsum);
	v_mfma_f32_16x16x32_bf16 v[50:53], v[66:69], v[62:65], v[50:53]
	v_fma_f32 v62, -v40, v45, v44
	v_fmac_f32_e32 v45, v62, v43
	v_fma_f32 v40, -v40, v45, v44
	v_div_fmas_f32 v40, v40, v43, v45
	v_div_fixup_f32 v44, v40, v41, 1.0
	v_add_u32_e32 v40, s46, v83
	v_lshlrev_b32_e32 v40, s52, v40
	v_add_u32_e32 v40, s0, v40
	v_mov_b64_e32 v[62:63], s[42:43]
	v_mad_i64_i32 v[62:63], s[0:1], v40, s66, v[62:63]
	s_lshl_b32 s0, s41, 6
	s_ashr_i32 s1, s0, 31
	v_lshl_add_u64 v[62:63], s[0:1], 1, v[62:63]
	v_pk_mul_f32 v[46:47], v[44:45], v[46:47] op_sel_hi:[0,1]
	v_pk_mul_f32 v[48:49], v[44:45], v[48:49] op_sel_hi:[0,1]
	v_lshl_add_u64 v[62:63], v[62:63], 0, v[90:91]
	v_cvt_pk_bf16_f32 v46, v46, v47
	v_cvt_pk_bf16_f32 v47, v48, v49
	global_store_dwordx2 v[62:63], v[46:47], off
	v_pk_mul_f32 v[46:47], v[44:45], v[54:55] op_sel_hi:[0,1]
	v_pk_mul_f32 v[48:49], v[44:45], v[56:57] op_sel_hi:[0,1]
	v_cvt_pk_bf16_f32 v46, v46, v47
	v_cvt_pk_bf16_f32 v47, v48, v49
	global_store_dwordx2 v[62:63], v[46:47], off offset:32
	v_pk_mul_f32 v[46:47], v[44:45], v[58:59] op_sel_hi:[0,1]
	v_pk_mul_f32 v[48:49], v[44:45], v[60:61] op_sel_hi:[0,1]
	v_cvt_pk_bf16_f32 v46, v46, v47
	v_cvt_pk_bf16_f32 v47, v48, v49
	global_store_dwordx2 v[62:63], v[46:47], off offset:64
	v_pk_mul_f32 v[46:47], v[44:45], v[50:51] op_sel_hi:[0,1]
	v_pk_mul_f32 v[44:45], v[44:45], v[52:53] op_sel_hi:[0,1]
	v_cvt_pk_bf16_f32 v46, v46, v47
	v_cvt_pk_bf16_f32 v47, v44, v45
	global_store_dwordx2 v[62:63], v[46:47], off offset:96
	s_and_saveexec_b64 s[0:1], s[20:21]
	s_cbranch_execz .LBB0_344
	v_cmp_gt_f32_e32 vcc, s54, v41
	s_ashr_i32 s41, s40, 31
	s_lshl_b64 s[40:41], s[40:41], 19
	v_cndmask_b32_e64 v43, 0, 32, vcc
	v_ldexp_f32 v41, v41, v43
	v_log_f32_e32 v43, v41
	v_readlane_b32 s46, v255, 43
	v_cndmask_b32_e32 v44, 0, v225, vcc
	s_add_u32 s40, s46, s40
	v_mul_f32_e32 v45, 0x3f317217, v43
	v_fma_f32 v45, v43, s56, -v45
	v_fmac_f32_e32 v45, 0x3377d1cf, v43
	v_fmac_f32_e32 v45, 0x3f317217, v43
	v_cmp_lt_f32_e64 vcc, |v43|, s57
	v_readlane_b32 s46, v255, 44
	v_ashrrev_i32_e32 v41, 31, v40
	v_cndmask_b32_e32 v43, v43, v45, vcc
	s_addc_u32 s41, s46, s41
	s_lshr_b32 s36, s36, 3
	v_sub_f32_e32 v43, v43, v44
	v_lshl_add_u64 v[40:41], v[40:41], 4, s[40:41]
	s_and_b32 s36, s36, 12
	v_add_f32_e32 v42, v42, v43
	v_lshl_add_u64 v[40:41], v[40:41], 0, s[36:37]
	global_store_dword v[40:41], v42, off
	s_branch .LBB0_344
